# EpiGlu: first-half residual loads merged into 4 dwordx4 as well
# baseline (speedup 1.0000x reference)
.LBB0_1529:
	s_mov_b32 s0, s40
	s_lshl_b32 s1, s22, 7
	v_mov_b32_e32 v154, v182
	v_mov_b32_e32 v160, v183
	s_or_b32 s1, s1, s48
	s_lshl_b32 s0, s0, 8
	v_lshl_add_u32 v152, v160, 2, s1
	v_ashrrev_i32_e32 v153, 31, v152
	v_lshlrev_b64 v[80:81], 2, v[152:153]
	v_lshl_add_u64 v[82:83], s[12:13], 0, v[80:81]
	v_lshl_add_u64 v[84:85], s[26:27], 0, v[80:81]
	global_load_dwordx4 v[100:103], v[84:85], off
	global_load_dwordx4 v[92:95], v[82:83], off
	s_nop 0
	global_load_dwordx4 v[80:83], v[82:83], off offset:256
	s_nop 0
	global_load_dwordx4 v[84:87], v[84:85], off offset:256
	s_add_i32 s0, s0, s45
	v_add_u32_e32 v156, s0, v154
	v_lshlrev_b64 v[190:191], 1, v[152:153]
	v_ashrrev_i32_e32 v157, 31, v156
	v_lshl_add_u64 v[154:155], s[16:17], 0, v[190:191]
	v_lshlrev_b64 v[192:193], 12, v[156:157]
	v_lshl_add_u64 v[158:159], v[154:155], 0, v[192:193]
	v_mbcnt_lo_u32_b32 v214, -1, 0
	v_mbcnt_hi_u32_b32 v214, -1, v214
	v_lshrrev_b32_e32 v214, 4, v214
	v_and_b32_e32 v214, 1, v214
	v_mul_u32_u24_e32 v214, 0x78, v214
	v_mov_b32_e32 v215, 0
	v_lshl_add_u64 v[242:243], v[158:159], 0, v[214:215]
	global_load_dwordx4 v[204:207], v[242:243], off
	v_add_u32_e32 v172, 16, v156
	v_add_u32_e32 v166, 32, v156
	v_add_u32_e32 v158, 48, v156
	v_ashrrev_i32_e32 v173, 31, v172
	v_ashrrev_i32_e32 v167, 31, v166
	v_ashrrev_i32_e32 v159, 31, v158
	v_lshlrev_b64 v[176:177], 12, v[172:173]
	v_lshlrev_b64 v[168:169], 12, v[166:167]
	v_cmp_eq_u32_e32 vcc, 0, v160
	v_lshlrev_b64 v[160:161], 12, v[158:159]
	v_lshl_add_u64 v[162:163], v[154:155], 0, v[176:177]
	v_lshl_add_u64 v[164:165], v[154:155], 0, v[168:169]
	v_lshl_add_u64 v[198:199], v[154:155], 0, v[160:161]
	v_lshl_add_u64 v[242:243], v[162:163], 0, v[214:215]
	global_load_dwordx4 v[208:211], v[242:243], off
	v_lshl_add_u64 v[242:243], v[164:165], 0, v[214:215]
	global_load_dwordx4 v[244:247], v[242:243], off
	s_nop 0
	v_lshl_add_u64 v[242:243], v[198:199], 0, v[214:215]
	global_load_dwordx4 v[248:251], v[242:243], off
	v_add_u32_e32 v216, 0x80, v156
	v_ashrrev_i32_e32 v217, 31, v216
	v_lshlrev_b64 v[216:217], 12, v[216:217]
	v_lshl_add_u64 v[216:217], v[154:155], 0, v[216:217]
	v_add_u32_e32 v218, 0x90, v156
	v_ashrrev_i32_e32 v219, 31, v218
	v_lshlrev_b64 v[218:219], 12, v[218:219]
	v_lshl_add_u64 v[218:219], v[154:155], 0, v[218:219]
	v_add_u32_e32 v220, 0xa0, v156
	v_ashrrev_i32_e32 v221, 31, v220
	v_lshlrev_b64 v[220:221], 12, v[220:221]
	v_lshl_add_u64 v[220:221], v[154:155], 0, v[220:221]
	v_add_u32_e32 v240, 0xb0, v156
	v_ashrrev_i32_e32 v241, 31, v240
	v_lshlrev_b64 v[240:241], 12, v[240:241]
	v_lshl_add_u64 v[240:241], v[154:155], 0, v[240:241]
	v_lshl_add_u64 v[216:217], v[216:217], 0, v[214:215]
	global_load_dwordx4 v[224:227], v[216:217], off
	v_lshl_add_u64 v[218:219], v[218:219], 0, v[214:215]
	global_load_dwordx4 v[228:231], v[218:219], off
	v_lshl_add_u64 v[220:221], v[220:221], 0, v[214:215]
	global_load_dwordx4 v[232:235], v[220:221], off
	v_lshl_add_u64 v[240:241], v[240:241], 0, v[214:215]
	global_load_dwordx4 v[236:239], v[240:241], off
	s_lshl_b32 s0, s22, 2
	s_ashr_i32 s1, s0, 31
	s_waitcnt vmcnt(4)
	v_permlane16_swap_b32_e32 v204, v206
	v_permlane16_swap_b32_e32 v205, v207
	v_permlane16_swap_b32_e32 v208, v210
	v_permlane16_swap_b32_e32 v209, v211
	v_permlane16_swap_b32_e32 v244, v246
	v_permlane16_swap_b32_e32 v245, v247
	v_permlane16_swap_b32_e32 v248, v250
	v_permlane16_swap_b32_e32 v249, v251
	v_mov_b32_e32 v194, v204
	v_mov_b32_e32 v195, v205
	v_mov_b32_e32 v196, v206
	v_mov_b32_e32 v197, v207
	v_mov_b32_e32 v180, v208
	v_mov_b32_e32 v181, v209
	v_mov_b32_e32 v178, v210
	v_mov_b32_e32 v179, v211
	v_mov_b32_e32 v174, v244
	v_mov_b32_e32 v175, v245
	v_mov_b32_e32 v170, v246
	v_mov_b32_e32 v171, v247
	v_mov_b32_e32 v164, v248
	v_mov_b32_e32 v165, v249
	v_mov_b32_e32 v162, v250
	v_mov_b32_e32 v163, v251
	v_add_f32_e32 v141, v141, v101
	v_add_f32_e32 v143, v143, v103
	v_add_f32_e32 v140, v140, v100
	v_add_f32_e32 v142, v142, v102
	v_add_f32_e32 v132, v132, v84
	v_mul_f32_e32 v141, 0xbfb8aa3b, v141
	v_mul_f32_e32 v143, 0xbfb8aa3b, v143
	v_mul_f32_e32 v140, 0xbfb8aa3b, v140
	v_mul_f32_e32 v142, 0xbfb8aa3b, v142
	v_mul_f32_e32 v132, 0xbfb8aa3b, v132
	v_exp_f32_e32 v141, v141
	v_exp_f32_e32 v143, v143
	v_exp_f32_e32 v140, v140
	v_exp_f32_e32 v142, v142
	v_exp_f32_e32 v132, v132
	v_add_f32_e32 v141, 1.0, v141
	v_add_f32_e32 v143, 1.0, v143
	v_add_f32_e32 v140, 1.0, v140
	v_add_f32_e32 v142, 1.0, v142
	v_add_f32_e32 v132, 1.0, v132
	v_rcp_f32_e32 v141, v141
	v_rcp_f32_e32 v143, v143
	v_add_f32_e32 v133, v133, v85
	v_rcp_f32_e32 v140, v140
	v_rcp_f32_e32 v142, v142
	v_rcp_f32_e32 v132, v132
	v_mul_f32_e32 v133, 0xbfb8aa3b, v133
	v_add_f32_e32 v137, v137, v93
	v_add_f32_e32 v139, v139, v95
	v_lshlrev_b32_e32 v189, 16, v194
	v_and_b32_e32 v194, 0xffff0000, v194
	v_lshlrev_b32_e32 v198, 16, v195
	v_and_b32_e32 v195, 0xffff0000, v195
	v_exp_f32_e32 v133, v133
	v_add_f32_e32 v136, v136, v92
	v_add_f32_e32 v138, v138, v94
	v_add_f32_e32 v128, v128, v80
	v_lshlrev_b32_e32 v199, 16, v196
	v_fmac_f32_e32 v194, v137, v141
	v_fmac_f32_e32 v195, v139, v143
	v_fmac_f32_e32 v189, v136, v140
	v_fmac_f32_e32 v198, v138, v142
	v_fmac_f32_e32 v199, v128, v132
	v_mul_f32_e32 v128, v194, v194
	v_mul_f32_e32 v132, v195, v195
	v_add_f32_e32 v134, v134, v86
	v_fmac_f32_e32 v128, v189, v189
	v_fmac_f32_e32 v132, v198, v198
	v_add_f32_e32 v133, 1.0, v133
	v_add_f32_e32 v128, v128, v132
	v_mul_f32_e32 v132, 0xbfb8aa3b, v134
	v_add_f32_e32 v134, v135, v87
	v_rcp_f32_e32 v133, v133
	v_exp_f32_e32 v132, v132
	v_mul_f32_e32 v134, 0xbfb8aa3b, v134
	v_exp_f32_e32 v134, v134
	v_add_f32_e32 v129, v129, v81
	v_and_b32_e32 v196, 0xffff0000, v196
	v_fmac_f32_e32 v196, v129, v133
	v_add_f32_e32 v129, 1.0, v132
	v_rcp_f32_e32 v129, v129
	v_add_f32_e32 v132, 1.0, v134
	v_rcp_f32_e32 v132, v132
	v_lshlrev_b32_e32 v200, 16, v197
	v_add_f32_e32 v130, v130, v82
	v_and_b32_e32 v197, 0xffff0000, v197
	v_fmac_f32_e32 v200, v130, v129
	v_add_f32_e32 v129, v131, v83
	v_fmac_f32_e32 v197, v129, v132
	v_mul_f32_e32 v129, v196, v196
	v_mul_f32_e32 v130, v197, v197
	v_fmac_f32_e32 v129, v199, v199
	v_fmac_f32_e32 v130, v200, v200
	v_add_f32_e32 v129, v129, v130
	v_and_b32_e32 v130, 64, v188
	v_add_f32_e32 v129, v128, v129
	v_xor_b32_e32 v128, 16, v188
	v_add_u32_e32 v136, 64, v130
	v_cmp_lt_i32_e64 s[2:3], v128, v136
	v_lshl_add_u64 v[130:131], s[16:17], 0, v[192:193]
	v_lshl_add_u64 v[134:135], v[130:131], 0, v[190:191]
	v_cndmask_b32_e64 v128, v188, v128, s[2:3]
	v_lshlrev_b32_e32 v128, 2, v128
	v_mov_b32_e32 v137, v129
	s_nop 1
	v_permlane16_swap_b32_e32 v137, v129
	v_cvt_pk_bf16_f32 v132, v189, v194
	v_cvt_pk_bf16_f32 v133, v198, v195
	v_mov_b32_e32 v204, v132
	v_mov_b32_e32 v205, v133
	v_cvt_pk_bf16_f32 v132, v199, v196
	s_waitcnt lgkmcnt(0)
	v_add_f32_e32 v130, v129, v137
	v_xor_b32_e32 v129, 32, v188
	v_cmp_lt_i32_e64 s[2:3], v129, v136
	v_cvt_pk_bf16_f32 v133, v200, v197
	v_mov_b32_e32 v206, v132
	v_mov_b32_e32 v207, v133
	v_lshl_add_u64 v[212:213], v[134:135], 0, v[214:215]
	s_nop 0
	v_permlane16_swap_b32_e32 v204, v206
	v_permlane16_swap_b32_e32 v205, v207
	global_store_dwordx4 v[212:213], v[204:207], off
	s_nop 0
	v_cndmask_b32_e64 v129, v188, v129, s[2:3]
	v_lshlrev_b32_e32 v129, 2, v129
	v_mov_b32_e32 v131, v130
	s_nop 1
	v_permlane32_swap_b32_e32 v131, v130
	s_and_saveexec_b64 s[2:3], vcc
	s_cbranch_execz .LBB0_1531
	s_waitcnt lgkmcnt(0)
	v_add_f32_e32 v132, v130, v131
	v_lshlrev_b64 v[130:131], 8, v[156:157]
	v_lshl_add_u64 v[130:131], s[18:19], 0, v[130:131]
	v_lshl_add_u64 v[130:131], s[0:1], 2, v[130:131]
	s_lshl_b32 s22, s44, 2
	v_lshl_add_u64 v[130:131], v[130:131], 0, s[22:23]
	global_store_dword v[130:131], v132, off
